# P0 gain-folded copy loops de-serialized (32 loads in flight, gain applied after LDS transpose) + P6 group-norm next-row prefetch
# speedup vs baseline: 1.0112x; 1.0112x over previous
; #define LDS_WAIT() asm volatile("s_waitcnt lgkmcnt(0)" ::: "memory")
; __device__ __forceinline__ void p0_item(const float* __restrict__ W, int ldw, int K, bf16_t* __restrict__ WT, int sc, int dn, int k0, const float* __restrict__ gk, LAS float* scr, int lane) {
;     ...
; #pragma unroll 8
;     for (int i = 0; i < 32; ++i) { const int kk = 2 * i + (lane >> 5); float v = __builtin_nontemporal_load(W + (size_t)(k0 + kk) * ldw + sc + (lane & 31)); if (gk) v *= gk[k0 + kk]; scr[kk * 33 + (lane & 31)] = v; }
;     LDS_WAIT(); asm volatile("" ::: "memory");
; __global__ void __launch_bounds__(NWAVES * 64, 2) mk_fwd(Args args) {
;     ...
;             if (r < I_UKV) { const int nblk = 4096 / 32, kb = r / nblk, nb = r % nblk; p0_item(in_w_ukv, 4096, 512, Wukv_t, nb * 32, nb * 32, kb * 64, in_kv_norm_g, scr, lane); continue; } r -= I_UKV;
.LBB0_59:
	s_andn2_b64 vcc, exec, s[12:13]
	s_cbranch_vccnz .LBB0_79
	s_lshr_b32 s12, s64, 1
	s_and_b32 s27, s12, 0x7fffffc0
	s_lshl_b64 s[12:13], s[64:65], 1
	s_waitcnt lgkmcnt(1)
	v_add_u32_e32 v6, s27, v16
	s_and_b32 s13, s13, 1
	s_and_b32 s12, s12, 0xffffff00
	s_waitcnt lgkmcnt(0)
	v_ashrrev_i32_e32 v7, 31, v6
	v_lshl_add_u64 v[2:3], v[54:55], 0, s[12:13]
	v_lshlrev_b64 v[4:5], 14, v[6:7]
	s_lshl_b32 s12, s25, 5
	v_or_b32_e32 v4, s26, v4
	v_readlane_b32 s44, v237, 3
	s_and_b32 s26, s12, 0xfe0
	v_readlane_b32 s58, v237, 17
	v_readlane_b32 s59, v237, 18
	s_lshl_b32 s68, s26, 2
	v_add_u32_e32 v0, s27, v100
	v_lshl_add_u64 v[4:5], v[44:45], 0, v[4:5]
	v_lshl_add_u64 v[6:7], v[6:7], 2, s[58:59]
	v_lshl_add_u64 v[8:9], v[44:45], 0, s[68:69]
	s_mov_b64 s[70:71], 0
	v_mov_b32_e32 v12, v109
	v_readlane_b32 s45, v237, 4
	v_readlane_b32 s46, v237, 5
	v_readlane_b32 s47, v237, 6
	v_readlane_b32 s48, v237, 7
	v_readlane_b32 s49, v237, 8
	v_readlane_b32 s50, v237, 9
	v_readlane_b32 s51, v237, 10
	v_readlane_b32 s52, v237, 11
	v_readlane_b32 s53, v237, 12
	v_readlane_b32 s54, v237, 13
	v_readlane_b32 s55, v237, 14
	v_readlane_b32 s56, v237, 15
	v_readlane_b32 s57, v237, 16
	s_lshl_b32 s12, s27, 2
	s_add_u32 s12, s58, s12
	s_addc_u32 s13, s59, 0
	v_lshlrev_b32_e32 v208, 5, v95
	v_mov_b32_e32 v209, 0
	v_lshl_add_u64 v[208:209], s[12:13], 0, v[208:209]
	global_load_dwordx4 v[210:213], v[208:209], off
	global_load_dwordx4 v[214:217], v[208:209], off offset:16
	v_add_u32_e32 v218, -12, v0
	v_ashrrev_i32_e32 v219, 31, v218
	v_lshlrev_b64 v[218:219], 14, v[218:219]
	v_lshl_add_u64 v[218:219], v[8:9], 0, v[218:219]
	v_add_u32_e32 v220, -10, v0
	v_ashrrev_i32_e32 v221, 31, v220
	v_lshlrev_b64 v[220:221], 14, v[220:221]
	v_lshl_add_u64 v[220:221], v[8:9], 0, v[220:221]
	v_add_u32_e32 v222, -8, v0
	v_ashrrev_i32_e32 v223, 31, v222
	v_lshlrev_b64 v[222:223], 14, v[222:223]
	v_lshl_add_u64 v[222:223], v[8:9], 0, v[222:223]
	v_add_u32_e32 v224, -6, v0
	v_ashrrev_i32_e32 v225, 31, v224
	v_lshlrev_b64 v[224:225], 14, v[224:225]
	v_lshl_add_u64 v[224:225], v[8:9], 0, v[224:225]
	v_add_u32_e32 v226, -4, v0
	v_ashrrev_i32_e32 v227, 31, v226
	v_lshlrev_b64 v[226:227], 14, v[226:227]
	v_lshl_add_u64 v[226:227], v[8:9], 0, v[226:227]
	v_add_u32_e32 v228, -2, v0
	v_ashrrev_i32_e32 v229, 31, v228
	v_lshlrev_b64 v[228:229], 14, v[228:229]
	v_lshl_add_u64 v[228:229], v[8:9], 0, v[228:229]
	v_add_u32_e32 v230, 0, v0
	v_ashrrev_i32_e32 v231, 31, v230
	v_lshlrev_b64 v[230:231], 14, v[230:231]
	v_lshl_add_u64 v[230:231], v[8:9], 0, v[230:231]
	global_load_dword v176, v[4:5], off nt
	global_load_dword v177, v[218:219], off nt
	global_load_dword v178, v[220:221], off nt
	global_load_dword v179, v[222:223], off nt
	global_load_dword v180, v[224:225], off nt
	global_load_dword v181, v[226:227], off nt
	global_load_dword v182, v[228:229], off nt
	global_load_dword v183, v[230:231], off nt
	v_add_u32_e32 v0, 16, v0
	v_lshl_add_u64 v[4:5], v[4:5], 0, s[42:43]
	s_add_u32 s70, s70, 64
	s_addc_u32 s71, s71, 0
	v_add_u32_e32 v218, -12, v0
	v_ashrrev_i32_e32 v219, 31, v218
	v_lshlrev_b64 v[218:219], 14, v[218:219]
	v_lshl_add_u64 v[218:219], v[8:9], 0, v[218:219]
	v_add_u32_e32 v220, -10, v0
	v_ashrrev_i32_e32 v221, 31, v220
	v_lshlrev_b64 v[220:221], 14, v[220:221]
	v_lshl_add_u64 v[220:221], v[8:9], 0, v[220:221]
	v_add_u32_e32 v222, -8, v0
	v_ashrrev_i32_e32 v223, 31, v222
	v_lshlrev_b64 v[222:223], 14, v[222:223]
	v_lshl_add_u64 v[222:223], v[8:9], 0, v[222:223]
	v_add_u32_e32 v224, -6, v0
	v_ashrrev_i32_e32 v225, 31, v224
	v_lshlrev_b64 v[224:225], 14, v[224:225]
	v_lshl_add_u64 v[224:225], v[8:9], 0, v[224:225]
	v_add_u32_e32 v226, -4, v0
	v_ashrrev_i32_e32 v227, 31, v226
	v_lshlrev_b64 v[226:227], 14, v[226:227]
	v_lshl_add_u64 v[226:227], v[8:9], 0, v[226:227]
	v_add_u32_e32 v228, -2, v0
	v_ashrrev_i32_e32 v229, 31, v228
	v_lshlrev_b64 v[228:229], 14, v[228:229]
	v_lshl_add_u64 v[228:229], v[8:9], 0, v[228:229]
	v_add_u32_e32 v230, 0, v0
	v_ashrrev_i32_e32 v231, 31, v230
	v_lshlrev_b64 v[230:231], 14, v[230:231]
	v_lshl_add_u64 v[230:231], v[8:9], 0, v[230:231]
	global_load_dword v184, v[4:5], off nt
	global_load_dword v185, v[218:219], off nt
	global_load_dword v186, v[220:221], off nt
	global_load_dword v187, v[222:223], off nt
	global_load_dword v188, v[224:225], off nt
	global_load_dword v189, v[226:227], off nt
	global_load_dword v190, v[228:229], off nt
	global_load_dword v191, v[230:231], off nt
	v_add_u32_e32 v0, 16, v0
	v_lshl_add_u64 v[4:5], v[4:5], 0, s[42:43]
	s_add_u32 s70, s70, 64
	s_addc_u32 s71, s71, 0
	v_add_u32_e32 v218, -12, v0
	v_ashrrev_i32_e32 v219, 31, v218
	v_lshlrev_b64 v[218:219], 14, v[218:219]
	v_lshl_add_u64 v[218:219], v[8:9], 0, v[218:219]
	v_add_u32_e32 v220, -10, v0
	v_ashrrev_i32_e32 v221, 31, v220
	v_lshlrev_b64 v[220:221], 14, v[220:221]
	v_lshl_add_u64 v[220:221], v[8:9], 0, v[220:221]
	v_add_u32_e32 v222, -8, v0
	v_ashrrev_i32_e32 v223, 31, v222
	v_lshlrev_b64 v[222:223], 14, v[222:223]
	v_lshl_add_u64 v[222:223], v[8:9], 0, v[222:223]
	v_add_u32_e32 v224, -6, v0
	v_ashrrev_i32_e32 v225, 31, v224
	v_lshlrev_b64 v[224:225], 14, v[224:225]
	v_lshl_add_u64 v[224:225], v[8:9], 0, v[224:225]
	v_add_u32_e32 v226, -4, v0
	v_ashrrev_i32_e32 v227, 31, v226
	v_lshlrev_b64 v[226:227], 14, v[226:227]
	v_lshl_add_u64 v[226:227], v[8:9], 0, v[226:227]
	v_add_u32_e32 v228, -2, v0
	v_ashrrev_i32_e32 v229, 31, v228
	v_lshlrev_b64 v[228:229], 14, v[228:229]
	v_lshl_add_u64 v[228:229], v[8:9], 0, v[228:229]
	v_add_u32_e32 v230, 0, v0
	v_ashrrev_i32_e32 v231, 31, v230
	v_lshlrev_b64 v[230:231], 14, v[230:231]
	v_lshl_add_u64 v[230:231], v[8:9], 0, v[230:231]
; #define LAS __attribute__((address_space(3)))
; #define LDS_WAIT() asm volatile("s_waitcnt lgkmcnt(0)" ::: "memory")
; __device__ __forceinline__ unsigned cvt_pk_bf16(float lo, float hi) { const f32x2 v = {lo, hi}; const bf16x2_t b = __builtin_convertvector(v, bf16x2_t); return __builtin_bit_cast(unsigned, b); }
; __device__ __forceinline__ void p0_item(const float* __restrict__ W, int ldw, int K, bf16_t* __restrict__ WT, int sc, int dn, int k0, const float* __restrict__ gk, LAS float* scr, int lane) {
;     ...
;     for (int i = 0; i < 32; ++i) { const int kk = 2 * i + (lane >> 5); float v = __builtin_nontemporal_load(W + (size_t)(k0 + kk) * ldw + sc + (lane & 31)); if (gk) v *= gk[k0 + kk]; scr[kk * 33 + (lane & 31)] = v; }
;     LDS_WAIT(); asm volatile("" ::: "memory");
; #pragma unroll
;     for (int j = 0; j < 4; ++j) { const int n = (lane >> 3) + 8 * j; const LAS float* s = scr + (8 * c) * 33 + n;
;         u32x4 o; o.x = cvt_pk_bf16(s[0 * 33], s[1 * 33]); o.y = cvt_pk_bf16(s[2 * 33], s[3 * 33]); o.z = cvt_pk_bf16(s[4 * 33], s[5 * 33]); o.w = cvt_pk_bf16(s[6 * 33], s[7 * 33]);
;         __builtin_nontemporal_store(o, (u32x4*)(WT + (size_t)(dn + n) * K + k0 + 8 * c)); }
	global_load_dword v192, v[4:5], off nt
	global_load_dword v193, v[218:219], off nt
	global_load_dword v194, v[220:221], off nt
	global_load_dword v195, v[222:223], off nt
	global_load_dword v196, v[224:225], off nt
	global_load_dword v197, v[226:227], off nt
	global_load_dword v198, v[228:229], off nt
	global_load_dword v199, v[230:231], off nt
	v_add_u32_e32 v0, 16, v0
	v_lshl_add_u64 v[4:5], v[4:5], 0, s[42:43]
	s_add_u32 s70, s70, 64
	s_addc_u32 s71, s71, 0
	v_add_u32_e32 v218, -12, v0
	v_ashrrev_i32_e32 v219, 31, v218
	v_lshlrev_b64 v[218:219], 14, v[218:219]
	v_lshl_add_u64 v[218:219], v[8:9], 0, v[218:219]
	v_add_u32_e32 v220, -10, v0
	v_ashrrev_i32_e32 v221, 31, v220
	v_lshlrev_b64 v[220:221], 14, v[220:221]
	v_lshl_add_u64 v[220:221], v[8:9], 0, v[220:221]
	v_add_u32_e32 v222, -8, v0
	v_ashrrev_i32_e32 v223, 31, v222
	v_lshlrev_b64 v[222:223], 14, v[222:223]
	v_lshl_add_u64 v[222:223], v[8:9], 0, v[222:223]
	v_add_u32_e32 v224, -6, v0
	v_ashrrev_i32_e32 v225, 31, v224
	v_lshlrev_b64 v[224:225], 14, v[224:225]
	v_lshl_add_u64 v[224:225], v[8:9], 0, v[224:225]
	v_add_u32_e32 v226, -4, v0
	v_ashrrev_i32_e32 v227, 31, v226
	v_lshlrev_b64 v[226:227], 14, v[226:227]
	v_lshl_add_u64 v[226:227], v[8:9], 0, v[226:227]
	v_add_u32_e32 v228, -2, v0
	v_ashrrev_i32_e32 v229, 31, v228
	v_lshlrev_b64 v[228:229], 14, v[228:229]
	v_lshl_add_u64 v[228:229], v[8:9], 0, v[228:229]
	v_add_u32_e32 v230, 0, v0
	v_ashrrev_i32_e32 v231, 31, v230
	v_lshlrev_b64 v[230:231], 14, v[230:231]
	v_lshl_add_u64 v[230:231], v[8:9], 0, v[230:231]
	global_load_dword v200, v[4:5], off nt
	global_load_dword v201, v[218:219], off nt
	global_load_dword v202, v[220:221], off nt
	global_load_dword v203, v[222:223], off nt
	global_load_dword v204, v[224:225], off nt
	global_load_dword v205, v[226:227], off nt
	global_load_dword v206, v[228:229], off nt
	global_load_dword v207, v[230:231], off nt
	v_add_u32_e32 v0, 16, v0
	v_lshl_add_u64 v[4:5], v[4:5], 0, s[42:43]
	s_add_u32 s70, s70, 64
	s_addc_u32 s71, s71, 0
	v_add_u32_e32 v13, 0x400, v12
	s_waitcnt vmcnt(30)
	ds_write2_b32 v12, v176, v177 offset1:66
	s_waitcnt vmcnt(28)
	ds_write2_b32 v12, v178, v179 offset0:132 offset1:198
	s_waitcnt vmcnt(26)
	ds_write2_b32 v13, v180, v181 offset0:8 offset1:74
	s_waitcnt vmcnt(24)
	ds_write2_b32 v13, v182, v183 offset0:140 offset1:206
	v_add_u32_e32 v12, 0x840, v12
	v_add_u32_e32 v13, 0x400, v12
	s_waitcnt vmcnt(22)
	ds_write2_b32 v12, v184, v185 offset1:66
	s_waitcnt vmcnt(20)
	ds_write2_b32 v12, v186, v187 offset0:132 offset1:198
	s_waitcnt vmcnt(18)
	ds_write2_b32 v13, v188, v189 offset0:8 offset1:74
	s_waitcnt vmcnt(16)
	ds_write2_b32 v13, v190, v191 offset0:140 offset1:206
	v_add_u32_e32 v12, 0x840, v12
	v_add_u32_e32 v13, 0x400, v12
	s_waitcnt vmcnt(14)
	ds_write2_b32 v12, v192, v193 offset1:66
	s_waitcnt vmcnt(12)
	ds_write2_b32 v12, v194, v195 offset0:132 offset1:198
	s_waitcnt vmcnt(10)
	ds_write2_b32 v13, v196, v197 offset0:8 offset1:74
	s_waitcnt vmcnt(8)
	ds_write2_b32 v13, v198, v199 offset0:140 offset1:206
	v_add_u32_e32 v12, 0x840, v12
	v_add_u32_e32 v13, 0x400, v12
	s_waitcnt vmcnt(6)
	ds_write2_b32 v12, v200, v201 offset1:66
	s_waitcnt vmcnt(4)
	ds_write2_b32 v12, v202, v203 offset0:132 offset1:198
	s_waitcnt vmcnt(2)
	ds_write2_b32 v13, v204, v205 offset0:8 offset1:74
	s_waitcnt vmcnt(0)
	ds_write2_b32 v13, v206, v207 offset0:140 offset1:206
	v_add_u32_e32 v12, 0x840, v12
.LBB0_78:
	s_waitcnt lgkmcnt(0)
	ds_read2_b32 v[4:5], v108 offset0:33 offset1:41
	ds_read2_b32 v[6:7], v108 offset1:8
	ds_read2_b32 v[8:9], v108 offset0:66 offset1:74
	ds_read2_b32 v[10:11], v108 offset0:99 offset1:107
	ds_read2_b32 v[12:13], v108 offset0:132 offset1:140
	ds_read2_b32 v[14:15], v108 offset0:165 offset1:173
	ds_read2_b32 v[64:65], v108 offset0:198 offset1:206
	ds_read2_b32 v[66:67], v108 offset0:231 offset1:239
	s_add_i32 s12, s25, 0xffff4c00
	v_add_u32_e32 v70, s26, v93
	s_and_b32 s68, s12, 0xffffff80
	v_ashrrev_i32_e32 v71, 31, v70
	v_lshl_add_u64 v[68:69], v[30:31], 0, s[68:69]
	v_lshlrev_b64 v[70:71], 10, v[70:71]
	s_waitcnt lgkmcnt(6)
	v_mul_f32_e32 v6, v6, v210
	v_mul_f32_e32 v4, v4, v211
	v_cvt_pk_bf16_f32 v0, v6, v4
	s_waitcnt lgkmcnt(4)
	v_mul_f32_e32 v8, v8, v212
	v_mul_f32_e32 v10, v10, v213
	v_cvt_pk_bf16_f32 v1, v8, v10
	s_waitcnt lgkmcnt(2)
	v_mul_f32_e32 v12, v12, v214
	v_mul_f32_e32 v14, v14, v215
	v_cvt_pk_bf16_f32 v2, v12, v14
	s_waitcnt lgkmcnt(0)
	v_mul_f32_e32 v64, v64, v216
	v_mul_f32_e32 v66, v66, v217
	v_cvt_pk_bf16_f32 v3, v64, v66
	v_lshl_add_u64 v[70:71], v[68:69], 0, v[70:71]
	v_add_u32_e32 v4, s26, v96
	global_store_dwordx4 v[70:71], v[0:3], off nt
	s_nop 1
	v_mul_f32_e32 v7, v7, v210
	v_mul_f32_e32 v5, v5, v211
	v_cvt_pk_bf16_f32 v0, v7, v5
	v_ashrrev_i32_e32 v5, 31, v4
	v_mul_f32_e32 v9, v9, v212
	v_mul_f32_e32 v11, v11, v213
	v_cvt_pk_bf16_f32 v1, v9, v11
	v_mul_f32_e32 v13, v13, v214
	v_mul_f32_e32 v15, v15, v215
	v_cvt_pk_bf16_f32 v2, v13, v15
	v_mul_f32_e32 v65, v65, v216
	v_mul_f32_e32 v67, v67, v217
	v_cvt_pk_bf16_f32 v3, v65, v67
	v_lshlrev_b64 v[4:5], 10, v[4:5]
	ds_read2_b32 v[6:7], v108 offset0:49 offset1:57
	ds_read2_b32 v[8:9], v108 offset0:16 offset1:24
	ds_read2_b32 v[10:11], v108 offset0:82 offset1:90
	ds_read2_b32 v[12:13], v108 offset0:115 offset1:123
	ds_read2_b32 v[14:15], v108 offset0:148 offset1:156
	ds_read2_b32 v[64:65], v108 offset0:181 offset1:189
	ds_read2_b32 v[66:67], v108 offset0:214 offset1:222
	ds_read2_b32 v[70:71], v108 offset0:247 offset1:255
	v_lshl_add_u64 v[4:5], v[68:69], 0, v[4:5]
	global_store_dwordx4 v[4:5], v[0:3], off nt
	v_add_u32_e32 v4, s26, v97
	v_ashrrev_i32_e32 v5, 31, v4
	v_lshlrev_b64 v[4:5], 10, v[4:5]
	s_waitcnt lgkmcnt(6)
	v_mul_f32_e32 v8, v8, v210
	v_mul_f32_e32 v6, v6, v211
	v_cvt_pk_bf16_f32 v0, v8, v6
	s_waitcnt lgkmcnt(4)
	v_mul_f32_e32 v10, v10, v212
	v_mul_f32_e32 v12, v12, v213
	v_cvt_pk_bf16_f32 v1, v10, v12
	s_waitcnt lgkmcnt(2)
	v_mul_f32_e32 v14, v14, v214
	v_mul_f32_e32 v64, v64, v215
	v_cvt_pk_bf16_f32 v2, v14, v64
	s_waitcnt lgkmcnt(0)
	v_mul_f32_e32 v66, v66, v216
	v_mul_f32_e32 v70, v70, v217
	v_cvt_pk_bf16_f32 v3, v66, v70
	v_lshl_add_u64 v[4:5], v[68:69], 0, v[4:5]
	global_store_dwordx4 v[4:5], v[0:3], off nt
	v_add_u32_e32 v4, s26, v98
	v_ashrrev_i32_e32 v5, 31, v4
	v_lshlrev_b64 v[4:5], 10, v[4:5]
	v_mul_f32_e32 v9, v9, v210
	v_mul_f32_e32 v7, v7, v211
	v_cvt_pk_bf16_f32 v0, v9, v7
	v_mul_f32_e32 v11, v11, v212
	v_mul_f32_e32 v13, v13, v213
	v_cvt_pk_bf16_f32 v1, v11, v13
	v_mul_f32_e32 v15, v15, v214
	v_mul_f32_e32 v65, v65, v215
	v_cvt_pk_bf16_f32 v2, v15, v65
	v_mul_f32_e32 v67, v67, v216
	v_mul_f32_e32 v71, v71, v217
	v_cvt_pk_bf16_f32 v3, v67, v71
	v_lshl_add_u64 v[4:5], v[68:69], 0, v[4:5]
	global_store_dwordx4 v[4:5], v[0:3], off nt
	s_waitcnt lgkmcnt(0)

; #define LDS_WAIT() asm volatile("s_waitcnt lgkmcnt(0)" ::: "memory")
; __device__ __forceinline__ void p0_item(const float* __restrict__ W, int ldw, int K, bf16_t* __restrict__ WT, int sc, int dn, int k0, const float* __restrict__ gk, LAS float* scr, int lane) {
;     ...
;     for (int i = 0; i < 32; ++i) { const int kk = 2 * i + (lane >> 5); float v = __builtin_nontemporal_load(W + (size_t)(k0 + kk) * ldw + sc + (lane & 31)); if (gk) v *= gk[k0 + kk]; scr[kk * 33 + (lane & 31)] = v; }
;     LDS_WAIT(); asm volatile("" ::: "memory");
; __global__ void __launch_bounds__(NWAVES * 64, 2) mk_fwd(Args args) {
;     ...
;             if (r < I_UQ) { const int nblk = 3072 / 32, kb = r / nblk, nb = r % nblk; p0_item(in_w_uq, 3072, 1024, Wuq_t, wuq_src(nb), nb * 32, kb * 64, in_q_norm_g, scr, lane); continue; } r -= I_UQ;
.LBB0_85:
	s_lshl_b32 s27, s27, 6
	s_and_b32 s29, s27, 0xffc0
	s_lshl_b64 s[12:13], s[68:69], 2
	v_add_u32_e32 v0, s29, v100
	v_mov_b64_e32 v[64:65], s[12:13]
	s_waitcnt lgkmcnt(2)
	v_mad_i64_i32 v[0:1], s[12:13], v0, s23, v[64:65]
	s_mul_hi_u32 s12, s28, 0x2aaaaab
	s_waitcnt lgkmcnt(0)
	v_add_u32_e32 v4, s29, v101
	v_add_u32_e32 v6, s29, v102
	v_add_u32_e32 v8, s29, v103
	v_add_u32_e32 v10, s29, v104
	v_add_u32_e32 v12, s29, v105
	v_add_u32_e32 v14, s29, v106
	v_add_u32_e32 v66, s29, v16
	v_readlane_b32 s44, v237, 3
	s_lshl_b32 s68, s12, 8
	v_mad_i64_i32 v[4:5], s[12:13], v4, s23, v[64:65]
	v_mad_i64_i32 v[6:7], s[12:13], v6, s23, v[64:65]
	v_mad_i64_i32 v[8:9], s[12:13], v8, s23, v[64:65]
	v_mad_i64_i32 v[10:11], s[12:13], v10, s23, v[64:65]
	v_mad_i64_i32 v[12:13], s[12:13], v12, s23, v[64:65]
	v_mad_i64_i32 v[14:15], s[12:13], v14, s23, v[64:65]
	v_ashrrev_i32_e32 v67, 31, v66
	v_mad_i64_i32 v[64:65], s[12:13], v66, s23, v[64:65]
	v_readlane_b32 s54, v237, 13
	v_readlane_b32 s55, v237, 14
	v_lshl_add_u64 v[0:1], v[56:57], 0, v[0:1]
	v_lshl_add_u64 v[2:3], v[52:53], 0, s[68:69]
	v_lshl_add_u64 v[4:5], v[56:57], 0, v[4:5]
	v_lshl_add_u64 v[6:7], v[56:57], 0, v[6:7]
	v_lshl_add_u64 v[8:9], v[56:57], 0, v[8:9]
	v_lshl_add_u64 v[10:11], v[56:57], 0, v[10:11]
	v_lshl_add_u64 v[12:13], v[56:57], 0, v[12:13]
	v_lshl_add_u64 v[14:15], v[56:57], 0, v[14:15]
	v_lshl_add_u64 v[64:65], v[56:57], 0, v[64:65]
	v_lshlrev_b64 v[66:67], 2, v[66:67]
	s_mov_b64 s[70:71], 0
	s_mov_b64 s[36:37], s[54:55]
	v_mov_b32_e32 v70, v109
	v_readlane_b32 s45, v237, 4
	v_readlane_b32 s46, v237, 5
	v_readlane_b32 s47, v237, 6
	v_readlane_b32 s48, v237, 7
	v_readlane_b32 s49, v237, 8
	v_readlane_b32 s50, v237, 9
	v_readlane_b32 s51, v237, 10
	v_readlane_b32 s52, v237, 11
	v_readlane_b32 s53, v237, 12
	v_readlane_b32 s56, v237, 15
	v_readlane_b32 s57, v237, 16
	v_readlane_b32 s58, v237, 17
	v_readlane_b32 s59, v237, 18
	s_lshl_b32 s12, s29, 2
	s_add_u32 s12, s36, s12
	s_addc_u32 s13, s37, 0
	v_lshlrev_b32_e32 v208, 5, v95
	v_mov_b32_e32 v209, 0
	v_lshl_add_u64 v[208:209], s[12:13], 0, v[208:209]
	global_load_dwordx4 v[210:213], v[208:209], off
	global_load_dwordx4 v[214:217], v[208:209], off offset:16
	v_lshl_add_u64 v[218:219], v[64:65], 0, s[70:71]
	v_lshl_add_u64 v[220:221], v[14:15], 0, s[70:71]
	v_lshl_add_u64 v[222:223], v[12:13], 0, s[70:71]
	v_lshl_add_u64 v[224:225], v[10:11], 0, s[70:71]
	v_lshl_add_u64 v[226:227], v[8:9], 0, s[70:71]
	v_lshl_add_u64 v[228:229], v[6:7], 0, s[70:71]
	v_lshl_add_u64 v[230:231], v[4:5], 0, s[70:71]
	v_lshl_add_u64 v[232:233], v[0:1], 0, s[70:71]
	global_load_dword v176, v[218:219], off nt
	global_load_dword v177, v[220:221], off nt
	global_load_dword v178, v[222:223], off nt
	global_load_dword v179, v[224:225], off nt
	global_load_dword v180, v[226:227], off nt
	global_load_dword v181, v[228:229], off nt
	global_load_dword v182, v[230:231], off nt
	global_load_dword v183, v[232:233], off nt
	s_add_u32 s70, s70, 0x30000
	s_addc_u32 s71, s71, 0
	s_add_u32 s36, s36, 64
	s_addc_u32 s37, s37, 0
	v_lshl_add_u64 v[218:219], v[64:65], 0, s[70:71]
	v_lshl_add_u64 v[220:221], v[14:15], 0, s[70:71]
	v_lshl_add_u64 v[222:223], v[12:13], 0, s[70:71]
	v_lshl_add_u64 v[224:225], v[10:11], 0, s[70:71]
	v_lshl_add_u64 v[226:227], v[8:9], 0, s[70:71]
	v_lshl_add_u64 v[228:229], v[6:7], 0, s[70:71]
	v_lshl_add_u64 v[230:231], v[4:5], 0, s[70:71]
	v_lshl_add_u64 v[232:233], v[0:1], 0, s[70:71]
	global_load_dword v184, v[218:219], off nt
	global_load_dword v185, v[220:221], off nt
	global_load_dword v186, v[222:223], off nt
	global_load_dword v187, v[224:225], off nt
	global_load_dword v188, v[226:227], off nt
	global_load_dword v189, v[228:229], off nt
	global_load_dword v190, v[230:231], off nt
	global_load_dword v191, v[232:233], off nt
	s_add_u32 s70, s70, 0x30000
	s_addc_u32 s71, s71, 0
	s_add_u32 s36, s36, 64
	s_addc_u32 s37, s37, 0
	v_lshl_add_u64 v[218:219], v[64:65], 0, s[70:71]
	v_lshl_add_u64 v[220:221], v[14:15], 0, s[70:71]
	v_lshl_add_u64 v[222:223], v[12:13], 0, s[70:71]
	v_lshl_add_u64 v[224:225], v[10:11], 0, s[70:71]
	v_lshl_add_u64 v[226:227], v[8:9], 0, s[70:71]
	v_lshl_add_u64 v[228:229], v[6:7], 0, s[70:71]
	v_lshl_add_u64 v[230:231], v[4:5], 0, s[70:71]
	v_lshl_add_u64 v[232:233], v[0:1], 0, s[70:71]
	global_load_dword v192, v[218:219], off nt
	global_load_dword v193, v[220:221], off nt
	global_load_dword v194, v[222:223], off nt
	global_load_dword v195, v[224:225], off nt
	global_load_dword v196, v[226:227], off nt
	global_load_dword v197, v[228:229], off nt
	global_load_dword v198, v[230:231], off nt
	global_load_dword v199, v[232:233], off nt
	s_add_u32 s70, s70, 0x30000
	s_addc_u32 s71, s71, 0
	s_add_u32 s36, s36, 64
	s_addc_u32 s37, s37, 0
	v_lshl_add_u64 v[218:219], v[64:65], 0, s[70:71]
	v_lshl_add_u64 v[220:221], v[14:15], 0, s[70:71]
	v_lshl_add_u64 v[222:223], v[12:13], 0, s[70:71]
	v_lshl_add_u64 v[224:225], v[10:11], 0, s[70:71]
	v_lshl_add_u64 v[226:227], v[8:9], 0, s[70:71]
	v_lshl_add_u64 v[228:229], v[6:7], 0, s[70:71]
	v_lshl_add_u64 v[230:231], v[4:5], 0, s[70:71]
	v_lshl_add_u64 v[232:233], v[0:1], 0, s[70:71]
	global_load_dword v200, v[218:219], off nt
	global_load_dword v201, v[220:221], off nt
	global_load_dword v202, v[222:223], off nt
	global_load_dword v203, v[224:225], off nt
	global_load_dword v204, v[226:227], off nt
	global_load_dword v205, v[228:229], off nt
	global_load_dword v206, v[230:231], off nt
	global_load_dword v207, v[232:233], off nt
	s_add_u32 s70, s70, 0x30000
	s_addc_u32 s71, s71, 0
	s_add_u32 s36, s36, 64
	s_addc_u32 s37, s37, 0
	v_add_u32_e32 v71, 0x400, v70
	s_waitcnt vmcnt(30)
	ds_write2_b32 v70, v176, v177 offset1:66
	s_waitcnt vmcnt(28)
	ds_write2_b32 v70, v178, v179 offset0:132 offset1:198
	s_waitcnt vmcnt(26)
	ds_write2_b32 v71, v180, v181 offset0:8 offset1:74
	s_waitcnt vmcnt(24)
	ds_write2_b32 v71, v182, v183 offset0:140 offset1:206
	v_add_u32_e32 v70, 0x840, v70
	v_add_u32_e32 v71, 0x400, v70
	s_waitcnt vmcnt(22)
	ds_write2_b32 v70, v184, v185 offset1:66
	s_waitcnt vmcnt(20)
	ds_write2_b32 v70, v186, v187 offset0:132 offset1:198
	s_waitcnt vmcnt(18)
	ds_write2_b32 v71, v188, v189 offset0:8 offset1:74
	s_waitcnt vmcnt(16)
	ds_write2_b32 v71, v190, v191 offset0:140 offset1:206
	v_add_u32_e32 v70, 0x840, v70
	v_add_u32_e32 v71, 0x400, v70
	s_waitcnt vmcnt(14)
	ds_write2_b32 v70, v192, v193 offset1:66
	s_waitcnt vmcnt(12)
	ds_write2_b32 v70, v194, v195 offset0:132 offset1:198
	s_waitcnt vmcnt(10)
	ds_write2_b32 v71, v196, v197 offset0:8 offset1:74
	s_waitcnt vmcnt(8)
	ds_write2_b32 v71, v198, v199 offset0:140 offset1:206
	v_add_u32_e32 v70, 0x840, v70
	v_add_u32_e32 v71, 0x400, v70
	s_waitcnt vmcnt(6)
	ds_write2_b32 v70, v200, v201 offset1:66
	s_waitcnt vmcnt(4)
	ds_write2_b32 v70, v202, v203 offset0:132 offset1:198
	s_waitcnt vmcnt(2)
	ds_write2_b32 v71, v204, v205 offset0:8 offset1:74
	s_waitcnt vmcnt(0)
	ds_write2_b32 v71, v206, v207 offset0:140 offset1:206
	v_add_u32_e32 v70, 0x840, v70
; #define LAS __attribute__((address_space(3)))
; #define LDS_WAIT() asm volatile("s_waitcnt lgkmcnt(0)" ::: "memory")
; __device__ __forceinline__ unsigned cvt_pk_bf16(float lo, float hi) { const f32x2 v = {lo, hi}; const bf16x2_t b = __builtin_convertvector(v, bf16x2_t); return __builtin_bit_cast(unsigned, b); }
; __device__ __forceinline__ void p0_item(const float* __restrict__ W, int ldw, int K, bf16_t* __restrict__ WT, int sc, int dn, int k0, const float* __restrict__ gk, LAS float* scr, int lane) {
;     ...
;     for (int i = 0; i < 32; ++i) { const int kk = 2 * i + (lane >> 5); float v = __builtin_nontemporal_load(W + (size_t)(k0 + kk) * ldw + sc + (lane & 31)); if (gk) v *= gk[k0 + kk]; scr[kk * 33 + (lane & 31)] = v; }
;     LDS_WAIT(); asm volatile("" ::: "memory");
; #pragma unroll
;     for (int j = 0; j < 4; ++j) { const int n = (lane >> 3) + 8 * j; const LAS float* s = scr + (8 * c) * 33 + n;
;         u32x4 o; o.x = cvt_pk_bf16(s[0 * 33], s[1 * 33]); o.y = cvt_pk_bf16(s[2 * 33], s[3 * 33]); o.z = cvt_pk_bf16(s[4 * 33], s[5 * 33]); o.w = cvt_pk_bf16(s[6 * 33], s[7 * 33]);
;         __builtin_nontemporal_store(o, (u32x4*)(WT + (size_t)(dn + n) * K + k0 + 8 * c)); }
.LBB0_103:
	s_waitcnt lgkmcnt(0)
	ds_read2_b32 v[4:5], v108 offset0:33 offset1:41
	ds_read2_b32 v[6:7], v108 offset1:8
	ds_read2_b32 v[8:9], v108 offset0:66 offset1:74
	ds_read2_b32 v[10:11], v108 offset0:99 offset1:107
	ds_read2_b32 v[12:13], v108 offset0:132 offset1:140
	ds_read2_b32 v[14:15], v108 offset0:165 offset1:173
	ds_read2_b32 v[64:65], v108 offset0:198 offset1:206
	ds_read2_b32 v[66:67], v108 offset0:231 offset1:239
	s_and_b32 s12, 0xffff, s27
	v_add_u32_e32 v70, s26, v93
	s_lshl_b32 s68, s12, 1
	v_ashrrev_i32_e32 v71, 31, v70
	v_lshl_add_u64 v[68:69], v[32:33], 0, s[68:69]
	v_lshlrev_b64 v[70:71], 11, v[70:71]
	s_waitcnt lgkmcnt(6)
	v_mul_f32_e32 v6, v6, v210
	v_mul_f32_e32 v4, v4, v211
	v_cvt_pk_bf16_f32 v0, v6, v4
	s_waitcnt lgkmcnt(4)
	v_mul_f32_e32 v8, v8, v212
	v_mul_f32_e32 v10, v10, v213
	v_cvt_pk_bf16_f32 v1, v8, v10
	s_waitcnt lgkmcnt(2)
	v_mul_f32_e32 v12, v12, v214
	v_mul_f32_e32 v14, v14, v215
	v_cvt_pk_bf16_f32 v2, v12, v14
	s_waitcnt lgkmcnt(0)
	v_mul_f32_e32 v64, v64, v216
	v_mul_f32_e32 v66, v66, v217
	v_cvt_pk_bf16_f32 v3, v64, v66
	v_lshl_add_u64 v[70:71], v[68:69], 0, v[70:71]
	v_add_u32_e32 v4, s26, v96
	global_store_dwordx4 v[70:71], v[0:3], off nt
	s_nop 1
	v_mul_f32_e32 v7, v7, v210
	v_mul_f32_e32 v5, v5, v211
	v_cvt_pk_bf16_f32 v0, v7, v5
	v_ashrrev_i32_e32 v5, 31, v4
	v_mul_f32_e32 v9, v9, v212
	v_mul_f32_e32 v11, v11, v213
	v_cvt_pk_bf16_f32 v1, v9, v11
	v_mul_f32_e32 v13, v13, v214
	v_mul_f32_e32 v15, v15, v215
	v_cvt_pk_bf16_f32 v2, v13, v15
	v_mul_f32_e32 v65, v65, v216
	v_mul_f32_e32 v67, v67, v217
	v_cvt_pk_bf16_f32 v3, v65, v67
	v_lshlrev_b64 v[4:5], 11, v[4:5]
	ds_read2_b32 v[6:7], v108 offset0:49 offset1:57
	ds_read2_b32 v[8:9], v108 offset0:16 offset1:24
	ds_read2_b32 v[10:11], v108 offset0:82 offset1:90
	ds_read2_b32 v[12:13], v108 offset0:115 offset1:123
	ds_read2_b32 v[14:15], v108 offset0:148 offset1:156
	ds_read2_b32 v[64:65], v108 offset0:181 offset1:189
	ds_read2_b32 v[66:67], v108 offset0:214 offset1:222
	ds_read2_b32 v[70:71], v108 offset0:247 offset1:255
	v_lshl_add_u64 v[4:5], v[68:69], 0, v[4:5]
	global_store_dwordx4 v[4:5], v[0:3], off nt
	v_add_u32_e32 v4, s26, v97
	v_ashrrev_i32_e32 v5, 31, v4
	v_lshlrev_b64 v[4:5], 11, v[4:5]
	s_waitcnt lgkmcnt(6)
	v_mul_f32_e32 v8, v8, v210
	v_mul_f32_e32 v6, v6, v211
	v_cvt_pk_bf16_f32 v0, v8, v6
	s_waitcnt lgkmcnt(4)
	v_mul_f32_e32 v10, v10, v212
	v_mul_f32_e32 v12, v12, v213
	v_cvt_pk_bf16_f32 v1, v10, v12
	s_waitcnt lgkmcnt(2)
	v_mul_f32_e32 v14, v14, v214
	v_mul_f32_e32 v64, v64, v215
	v_cvt_pk_bf16_f32 v2, v14, v64
	s_waitcnt lgkmcnt(0)
	v_mul_f32_e32 v66, v66, v216
	v_mul_f32_e32 v70, v70, v217
	v_cvt_pk_bf16_f32 v3, v66, v70
	v_lshl_add_u64 v[4:5], v[68:69], 0, v[4:5]
	global_store_dwordx4 v[4:5], v[0:3], off nt
	v_add_u32_e32 v4, s26, v98
	v_ashrrev_i32_e32 v5, 31, v4
	v_lshlrev_b64 v[4:5], 11, v[4:5]
	v_mul_f32_e32 v9, v9, v210
	v_mul_f32_e32 v7, v7, v211
	v_cvt_pk_bf16_f32 v0, v9, v7
	v_mul_f32_e32 v11, v11, v212
	v_mul_f32_e32 v13, v13, v213
	v_cvt_pk_bf16_f32 v1, v11, v13
	v_mul_f32_e32 v15, v15, v214
	v_mul_f32_e32 v65, v65, v215
	v_cvt_pk_bf16_f32 v2, v15, v65
	v_mul_f32_e32 v67, v67, v216
	v_mul_f32_e32 v71, v71, v217
	v_cvt_pk_bf16_f32 v3, v67, v71
	v_lshl_add_u64 v[4:5], v[68:69], 0, v[4:5]
	global_store_dwordx4 v[4:5], v[0:3], off nt
	s_waitcnt lgkmcnt(0)

; __device__ __forceinline__ unsigned cvt_pk_bf16(float lo, float hi) { const f32x2 v = {lo, hi}; const bf16x2_t b = __builtin_convertvector(v, bf16x2_t); return __builtin_bit_cast(unsigned, b); }
; __device__ __forceinline__ float bf_lo(unsigned w) { return __uint_as_float(w << 16); }
; __device__ __forceinline__ float bf_hi(unsigned w) { return __uint_as_float(w & 0xffff0000u); }
; __global__ void __launch_bounds__(NWAVES * 64, 2) mk_fwd(Args args) {
;     ...
;         for (int it = gw; it < T * 8; it += NGW) {
;             const size_t off = (size_t)it * 512;
;             const u32x2 aw = __builtin_nontemporal_load((const u32x2*)(ORET + off + lane * 4)), bw = __builtin_nontemporal_load((const u32x2*)(ORET + off + 256 + lane * 4));
;             const f32x4 a = {bf_lo(aw.x), bf_hi(aw.x), bf_lo(aw.y), bf_hi(aw.y)}, b = {bf_lo(bw.x), bf_hi(bw.x), bf_lo(bw.y), bf_hi(bw.y)};
;             const float mean = wave_sum((a[0] + a[1]) + (a[2] + a[3]) + (b[0] + b[1]) + (b[2] + b[3])) * (1.0f / 512.0f);
;             const f32x4 da = a - mean, db = b - mean;
;             const float var = wave_sum((da[0] * da[0] + da[1] * da[1]) + (da[2] * da[2] + da[3] * da[3]) + (db[0] * db[0] + db[1] * db[1]) + (db[2] * db[2] + db[3] * db[3])) * (1.0f / 512.0f);
;             const float rstd = rsqrtf(var + LN_EPS);
;             const size_t goff = (size_t)(it >> 3) * RGP + (it & 7) * 512;
;             const u32x2 ga = __builtin_nontemporal_load((const u32x2*)(RG + goff + lane * 4)), gb = __builtin_nontemporal_load((const u32x2*)(RG + goff + 256 + lane * 4));
;             u32x2 oa, ob;
;             oa.x = cvt_pk_bf16(da[0] * rstd * bf_lo(ga.x), da[1] * rstd * bf_hi(ga.x)); oa.y = cvt_pk_bf16(da[2] * rstd * bf_lo(ga.y), da[3] * rstd * bf_hi(ga.y));
;             ob.x = cvt_pk_bf16(db[0] * rstd * bf_lo(gb.x), db[1] * rstd * bf_hi(gb.x)); ob.y = cvt_pk_bf16(db[2] * rstd * bf_lo(gb.y), db[3] * rstd * bf_hi(gb.y));
;             *(u32x2*)(ROUT + off + lane * 4) = oa; *(u32x2*)(ROUT + off + 256 + lane * 4) = ob;
.LBB0_644:
	s_cmp_lt_i32 s86, 7
	s_cselect_b64 s[0:1], -1, 0
	s_and_b64 s[2:3], s[0:1], s[2:3]
	s_andn2_b64 vcc, exec, s[2:3]
	s_cbranch_vccnz .LBB0_649
	s_cmp_gt_i32 s90, 0xffff
	v_mbcnt_lo_u32_b32 v0, -1, 0
	v_mbcnt_hi_u32_b32 v0, -1, v0
	s_cbranch_scc1 .LBB0_649
	v_mbcnt_lo_u32_b32 v2, -1, 0
	v_mbcnt_hi_u32_b32 v2, -1, v2
	v_and_b32_e32 v3, 64, v2
	v_add_u32_e32 v3, 64, v3
	v_xor_b32_e32 v4, 1, v2
	v_cmp_lt_i32_e32 vcc, v4, v3
	s_waitcnt lgkmcnt(0)
	v_xor_b32_e32 v5, 2, v2
	v_xor_b32_e32 v6, 4, v2
	v_cndmask_b32_e32 v4, v2, v4, vcc
	v_cmp_lt_i32_e32 vcc, v5, v3
	s_add_u32 s0, s78, 0x53700000
	v_xor_b32_e32 v7, 8, v2
	v_cndmask_b32_e32 v5, v2, v5, vcc
	v_cmp_lt_i32_e32 vcc, v6, v3
	s_addc_u32 s1, s79, 0
	v_xor_b32_e32 v8, 16, v2
	v_cndmask_b32_e32 v6, v2, v6, vcc
	v_cmp_lt_i32_e32 vcc, v7, v3
	s_ashr_i32 s91, s90, 31
	v_xor_b32_e32 v9, 32, v2
	v_cndmask_b32_e32 v7, v2, v7, vcc
	v_cmp_lt_i32_e32 vcc, v8, v3
	s_lshl_b64 s[4:5], s[90:91], 10
	v_lshlrev_b32_e32 v0, 2, v0
	v_cndmask_b32_e32 v8, v2, v8, vcc
	v_cmp_lt_i32_e32 vcc, v9, v3
	s_add_u32 s4, s78, s4
	v_ashrrev_i32_e32 v1, 31, v0
	v_cndmask_b32_e32 v2, v2, v9, vcc
	s_addc_u32 s5, s79, s5
	v_readlane_b32 s6, v237, 57
	v_lshlrev_b32_e32 v9, 2, v2
	v_lshl_add_u64 v[2:3], v[0:1], 1, s[4:5]
	s_mov_b64 s[4:5], 0x29e00000
	s_ashr_i32 s83, s82, 31
	s_lshl_b32 s6, s6, 12
	s_lshl_b32 s7, s93, 9
	v_lshlrev_b32_e32 v4, 2, v4
	v_lshlrev_b32_e32 v5, 2, v5
	v_lshlrev_b32_e32 v6, 2, v6
	v_lshlrev_b32_e32 v7, 2, v7
	v_lshlrev_b32_e32 v8, 2, v8
	v_lshl_add_u64 v[2:3], v[2:3], 0, s[4:5]
	s_lshl_b64 s[4:5], s[82:83], 10
	s_add_i32 s6, s6, s7
	s_lshl_b32 s7, s85, 12
	v_mov_b32_e32 v10, 0x3727c5ac
	s_mov_b32 s8, 0x800000
	s_mov_b32 s9, s90
	v_add_co_u32_e32 v38, vcc, 0xd8300000, v2
	s_nop 1
	v_addc_co_u32_e32 v39, vcc, -1, v3, vcc
	v_add_co_u32_e32 v40, vcc, 0xd8301000, v2
	s_nop 1
	v_addc_co_u32_e32 v41, vcc, -1, v3, vcc
	global_load_dwordx2 v[34:35], v[38:39], off nt
	global_load_dwordx2 v[36:37], v[40:41], off offset:-3584 nt
	s_waitcnt vmcnt(0)
.LBB0_647:
	s_waitcnt vmcnt(2)
	v_mov_b32_e32 v12, v34
	v_mov_b32_e32 v13, v35
	v_mov_b32_e32 v14, v36
	v_mov_b32_e32 v15, v37
	v_lshl_add_u64 v[38:39], v[2:3], 0, s[4:5]
	v_add_co_u32_e32 v40, vcc, 0xd8301000, v38
	s_ashr_i32 s10, s9, 3
	s_nop 0
	v_addc_co_u32_e32 v41, vcc, -1, v39, vcc
	v_add_co_u32_e32 v38, vcc, 0xd8300000, v38
	s_nop 1
	v_addc_co_u32_e32 v39, vcc, -1, v39, vcc
	global_load_dwordx2 v[34:35], v[38:39], off nt
	global_load_dwordx2 v[36:37], v[40:41], off offset:-3584 nt
	s_and_b32 s11, s6, 0xe00
	s_mul_hi_i32 s12, s10, 0x2080
	s_mulk_i32 s10, 0x2080
	s_add_u32 s10, s0, s10
	s_addc_u32 s12, s1, s12
	s_lshl_b32 s11, s11, 1
	s_add_u32 s10, s10, s11
	s_addc_u32 s11, s12, 0
	s_add_i32 s9, s9, s82
	s_add_i32 s6, s6, s7
	s_cmp_lt_i32 s9, 0x10000
	v_lshlrev_b32_e32 v17, 16, v13
	v_lshlrev_b32_e32 v16, 16, v12
	v_and_b32_e32 v13, 0xffff0000, v13
	v_and_b32_e32 v12, 0xffff0000, v12
	v_pk_add_f32 v[18:19], v[16:17], v[12:13]
	v_lshlrev_b32_e32 v21, 16, v15
	v_lshlrev_b32_e32 v20, 16, v14
	v_and_b32_e32 v15, 0xffff0000, v15
	v_and_b32_e32 v14, 0xffff0000, v14
	v_pk_add_f32 v[22:23], v[20:21], v[14:15]
	v_add_f32_e32 v11, v18, v19
	v_add_f32_e32 v11, v11, v22
	v_add_f32_e32 v11, v23, v11
	ds_bpermute_b32 v18, v4, v11
	s_waitcnt lgkmcnt(0)
	v_add_f32_e32 v11, v11, v18
	ds_bpermute_b32 v22, v5, v11
	v_lshl_add_u64 v[18:19], v[0:1], 1, s[10:11]
	s_waitcnt lgkmcnt(0)
	v_add_f32_e32 v11, v11, v22
	global_load_dwordx2 v[22:23], v[18:19], off nt
	s_nop 0
	global_load_dwordx2 v[18:19], v[18:19], off offset:512 nt
	ds_bpermute_b32 v24, v6, v11
	s_waitcnt lgkmcnt(0)
	v_add_f32_e32 v11, v11, v24
	ds_bpermute_b32 v24, v7, v11
	s_waitcnt lgkmcnt(0)
	v_add_f32_e32 v11, v11, v24
	ds_bpermute_b32 v24, v8, v11
	s_waitcnt lgkmcnt(0)
	v_add_f32_e32 v11, v11, v24
	ds_bpermute_b32 v24, v9, v11
	s_waitcnt lgkmcnt(0)
	v_add_f32_e32 v11, v11, v24
	v_fmac_f32_e32 v12, 0xbb000000, v11
	v_fmac_f32_e32 v13, 0xbb000000, v11
	v_fmac_f32_e32 v17, 0xbb000000, v11
	v_fmac_f32_e32 v16, 0xbb000000, v11
	v_fmac_f32_e32 v14, 0xbb000000, v11
	v_fmac_f32_e32 v15, 0xbb000000, v11
	v_fmac_f32_e32 v21, 0xbb000000, v11
	v_mov_b32_e32 v24, v17
	v_mov_b32_e32 v25, v13
	v_mov_b32_e32 v17, v12
	v_fmac_f32_e32 v20, 0xbb000000, v11
	v_mov_b32_e32 v12, v21
	v_mov_b32_e32 v13, v15
	v_mov_b32_e32 v21, v14
	v_pk_mul_f32 v[14:15], v[24:25], v[24:25]
	v_pk_mul_f32 v[26:27], v[16:17], v[16:17]
	v_pk_mul_f32 v[28:29], v[12:13], v[12:13]
	v_pk_mul_f32 v[30:31], v[20:21], v[20:21]
	v_pk_mov_b32 v[32:33], v[26:27], v[14:15] op_sel:[1,0]
	v_mov_b32_e32 v27, v15
	v_mov_b32_e32 v14, v28
	v_mov_b32_e32 v15, v30
	v_mov_b32_e32 v30, v29
	v_pk_add_f32 v[26:27], v[32:33], v[26:27]
	v_pk_add_f32 v[14:15], v[14:15], v[30:31]
	v_add_f32_e32 v11, v26, v27
	v_add_f32_e32 v11, v15, v11
	v_add_f32_e32 v11, v14, v11
	ds_bpermute_b32 v14, v4, v11
	s_waitcnt lgkmcnt(0)
	v_add_f32_e32 v11, v11, v14
	ds_bpermute_b32 v14, v5, v11
	s_waitcnt lgkmcnt(0)
	v_add_f32_e32 v11, v11, v14
	ds_bpermute_b32 v14, v6, v11
	s_waitcnt lgkmcnt(0)
	v_add_f32_e32 v11, v11, v14
	ds_bpermute_b32 v14, v7, v11
	s_waitcnt lgkmcnt(0)
	v_add_f32_e32 v11, v11, v14
	ds_bpermute_b32 v15, v8, v11
	s_waitcnt vmcnt(1)
	v_lshlrev_b32_e32 v14, 16, v22
	s_waitcnt vmcnt(0)
	v_lshlrev_b32_e32 v26, 16, v18
	s_waitcnt lgkmcnt(0)
	v_add_f32_e32 v11, v11, v15
	ds_bpermute_b32 v27, v9, v11
	v_and_b32_e32 v15, 0xffff0000, v22
	v_lshlrev_b32_e32 v22, 16, v23
	v_and_b32_e32 v23, 0xffff0000, v23
	s_waitcnt lgkmcnt(0)
	v_add_f32_e32 v11, v11, v27
	v_fmamk_f32 v11, v11, 0x3b000000, v10
	v_mul_f32_e32 v27, 0x4b800000, v11
	v_cmp_gt_f32_e32 vcc, s8, v11
	s_nop 1
	v_cndmask_b32_e32 v11, v11, v27, vcc
	v_rsq_f32_e32 v11, v11
	v_and_b32_e32 v27, 0xffff0000, v18
	v_lshlrev_b32_e32 v18, 16, v19
	v_and_b32_e32 v19, 0xffff0000, v19
	v_mul_f32_e32 v28, 0x45800000, v11
	v_cndmask_b32_e32 v28, v11, v28, vcc
	v_pk_mul_f32 v[16:17], v[16:17], v[28:29] op_sel_hi:[1,0]
	v_pk_mul_f32 v[24:25], v[24:25], v[28:29] op_sel_hi:[1,0]
	v_pk_mul_f32 v[20:21], v[20:21], v[28:29] op_sel_hi:[1,0]
	v_pk_mul_f32 v[12:13], v[12:13], v[28:29] op_sel_hi:[1,0]
	v_pk_mul_f32 v[14:15], v[16:17], v[14:15]
	v_pk_mul_f32 v[16:17], v[24:25], v[22:23]
	v_pk_mul_f32 v[20:21], v[20:21], v[26:27]
	v_pk_mul_f32 v[12:13], v[12:13], v[18:19]
	v_cvt_pk_bf16_f32 v14, v14, v15
	v_cvt_pk_bf16_f32 v15, v16, v17
	v_cvt_pk_bf16_f32 v16, v20, v21
	v_cvt_pk_bf16_f32 v17, v12, v13
	global_store_dwordx2 v[2:3], v[14:15], off
	global_store_dwordx2 v[2:3], v[16:17], off offset:512
	v_lshl_add_u64 v[2:3], v[2:3], 0, s[4:5]
	s_cbranch_scc1 .LBB0_647
	v_readlane_b32 s14, v236, 14
